# GEMM tile start: accumulator zeroing with 64 v_mov_b64 instead of 128 v_mov_b32
# baseline (speedup 1.0000x reference)
; template <class Epi>
; __device__ __forceinline__ void gemm_phase(LAS unsigned char* lds, const Gemm g, const StaticOrder S, const Epi E) {
;     ...
;         const bool has_next = S.next(ui + 1, nxt);
;         const bool nrev = has_next && ((ui + 1 + g.rev0) & 1);
;         ksn = has_next ? (nrev ? -(long)kstep : (long)kstep) : ksc;
;         const char* nA = has_next ? (const char*)g.A + (size_t)nxt.pm * tstepA + (size_t)nxt.pn * g.a_pn_off + (nrev ? klast : 0) : cA;
;         const char* nB = has_next ? (const char*)g.Bt + (size_t)nxt.pn * tstepB + (nrev ? klast : 0) : cB;
;     ...
; #pragma unroll
;         for (int a = 0; a < 2; ++a)
; #pragma unroll
;             for (int b = 0; b < 2; ++b)
; #pragma unroll
;                 for (int m = 0; m < 4; ++m)
; #pragma unroll
;                     for (int n = 0; n < 2; ++n) acc[a][b][m][n] = (f32x4){0.f, 0.f, 0.f, 0.f};
.LBB0_120:
	s_bitcmp0_b32 s11, 0
	s_cselect_b64 s[14:15], -1, 0
	s_and_b64 s[16:17], s[14:15], s[0:1]
	s_and_b64 s[14:15], s[16:17], exec
	s_cselect_b32 s15, -1, 0
	s_cselect_b32 s14, s56, 0x80
	s_and_b64 s[18:19], s[0:1], exec
	s_cselect_b32 s29, s15, s27
	s_cselect_b32 s28, s14, s26
	s_ashr_i32 s13, s12, 31
	s_lshl_b64 s[18:19], s[12:13], 20
	s_add_u32 s11, s76, s18
	s_addc_u32 s13, s77, s19
	s_and_b64 s[16:17], s[16:17], exec
	s_cselect_b32 s34, 0xf80, 0
	s_add_u32 s16, s11, s34
	s_addc_u32 s17, s13, 0
	s_and_b64 s[18:19], s[0:1], exec
	s_cselect_b32 s31, s17, s25
	s_cselect_b32 s30, s16, s24
	s_ashr_i32 s11, s10, 31
	s_lshl_b64 s[18:19], s[10:11], 20
	s_add_u32 s11, s82, s18
	s_addc_u32 s13, s83, s19
	s_add_u32 s18, s11, s34
	s_addc_u32 s19, s13, 0
	s_and_b64 s[34:35], s[0:1], exec
	v_mov_b64_e32 v[0:1], 0
	s_mov_b32 s62, 0
	s_cselect_b32 s35, s19, s23
	s_cselect_b32 s34, s18, s22
	v_mov_b64_e32 v[2:3], 0
	v_mov_b64_e32 v[4:5], 0
	v_mov_b64_e32 v[6:7], 0
	v_mov_b64_e32 v[16:17], 0
	v_mov_b64_e32 v[18:19], 0
	v_mov_b64_e32 v[20:21], 0
	v_mov_b64_e32 v[22:23], 0
	v_mov_b64_e32 v[32:33], 0
	v_mov_b64_e32 v[34:35], 0
	v_mov_b64_e32 v[36:37], 0
	v_mov_b64_e32 v[38:39], 0
	v_mov_b64_e32 v[48:49], 0
	v_mov_b64_e32 v[50:51], 0
	v_mov_b64_e32 v[52:53], 0
	v_mov_b64_e32 v[54:55], 0
	v_mov_b64_e32 v[8:9], 0
	v_mov_b64_e32 v[10:11], 0
	v_mov_b64_e32 v[12:13], 0
	v_mov_b64_e32 v[14:15], 0
	v_mov_b64_e32 v[24:25], 0
	v_mov_b64_e32 v[26:27], 0
	v_mov_b64_e32 v[28:29], 0
	v_mov_b64_e32 v[30:31], 0
	v_mov_b64_e32 v[40:41], 0
	v_mov_b64_e32 v[42:43], 0
	v_mov_b64_e32 v[44:45], 0
	v_mov_b64_e32 v[46:47], 0
	v_mov_b64_e32 v[56:57], 0
	v_mov_b64_e32 v[58:59], 0
	v_mov_b64_e32 v[60:61], 0
	v_mov_b64_e32 v[62:63], 0
	v_mov_b64_e32 v[64:65], 0
	v_mov_b64_e32 v[66:67], 0
	v_mov_b64_e32 v[68:69], 0
	v_mov_b64_e32 v[70:71], 0
	v_mov_b64_e32 v[80:81], 0
	v_mov_b64_e32 v[82:83], 0
	v_mov_b64_e32 v[84:85], 0
	v_mov_b64_e32 v[86:87], 0
	v_mov_b64_e32 v[96:97], 0
	v_mov_b64_e32 v[98:99], 0
	v_mov_b64_e32 v[100:101], 0
	v_mov_b64_e32 v[102:103], 0
	v_mov_b64_e32 v[120:121], 0
	v_mov_b64_e32 v[122:123], 0
	v_mov_b64_e32 v[124:125], 0
	v_mov_b64_e32 v[126:127], 0
	v_mov_b64_e32 v[72:73], 0
	v_mov_b64_e32 v[74:75], 0
	v_mov_b64_e32 v[76:77], 0
	v_mov_b64_e32 v[78:79], 0
	v_mov_b64_e32 v[88:89], 0
	v_mov_b64_e32 v[90:91], 0
	v_mov_b64_e32 v[92:93], 0
	v_mov_b64_e32 v[94:95], 0
	v_mov_b64_e32 v[104:105], 0
	v_mov_b64_e32 v[106:107], 0
	v_mov_b64_e32 v[108:109], 0
	v_mov_b64_e32 v[110:111], 0
	v_mov_b64_e32 v[112:113], 0
	v_mov_b64_e32 v[114:115], 0
	v_mov_b64_e32 v[116:117], 0
	v_mov_b64_e32 v[118:119], 0
	s_branch .LBB0_122

; template <class Epi>
; __device__ __forceinline__ void gemm_phase(LAS unsigned char* lds, const Gemm g, const StaticOrder S, const Epi E) {
;     ...
;         const bool has_next = S.next(ui + 1, nxt);
;         const bool nrev = has_next && ((ui + 1 + g.rev0) & 1);
;         ksn = has_next ? (nrev ? -(long)kstep : (long)kstep) : ksc;
;         const char* nA = has_next ? (const char*)g.A + (size_t)nxt.pm * tstepA + (size_t)nxt.pn * g.a_pn_off + (nrev ? klast : 0) : cA;
;         const char* nB = has_next ? (const char*)g.Bt + (size_t)nxt.pn * tstepB + (nrev ? klast : 0) : cB;
;     ...
; #pragma unroll
;         for (int a = 0; a < 2; ++a)
; #pragma unroll
;             for (int b = 0; b < 2; ++b)
; #pragma unroll
;                 for (int m = 0; m < 4; ++m)
; #pragma unroll
;                     for (int n = 0; n < 2; ++n) acc[a][b][m][n] = (f32x4){0.f, 0.f, 0.f, 0.f};
.LBB0_205:
	s_and_b64 s[26:27], s[26:27], exec
	s_cselect_b32 s27, 0, -1
	s_cselect_b32 s26, s58, 0xffffff80
	s_and_b64 s[4:5], s[4:5], exec
	v_mov_b64_e32 v[0:1], 0
	s_mov_b32 s70, 0
	s_cselect_b32 s5, s27, s35
	s_cselect_b32 s4, s26, s34
	s_waitcnt lgkmcnt(0)
	v_mov_b64_e32 v[2:3], 0
	v_mov_b64_e32 v[4:5], 0
	v_mov_b64_e32 v[6:7], 0
	v_mov_b64_e32 v[16:17], 0
	v_mov_b64_e32 v[18:19], 0
	v_mov_b64_e32 v[20:21], 0
	v_mov_b64_e32 v[22:23], 0
	v_mov_b64_e32 v[32:33], 0
	v_mov_b64_e32 v[34:35], 0
	v_mov_b64_e32 v[36:37], 0
	v_mov_b64_e32 v[38:39], 0
	v_mov_b64_e32 v[48:49], 0
	v_mov_b64_e32 v[50:51], 0
	v_mov_b64_e32 v[52:53], 0
	v_mov_b64_e32 v[54:55], 0
	v_mov_b64_e32 v[8:9], 0
	v_mov_b64_e32 v[10:11], 0
	v_mov_b64_e32 v[12:13], 0
	v_mov_b64_e32 v[14:15], 0
	v_mov_b64_e32 v[24:25], 0
	v_mov_b64_e32 v[26:27], 0
	v_mov_b64_e32 v[28:29], 0
	v_mov_b64_e32 v[30:31], 0
	v_mov_b64_e32 v[40:41], 0
	v_mov_b64_e32 v[42:43], 0
	v_mov_b64_e32 v[44:45], 0
	v_mov_b64_e32 v[46:47], 0
	v_mov_b64_e32 v[56:57], 0
	v_mov_b64_e32 v[58:59], 0
	v_mov_b64_e32 v[60:61], 0
	v_mov_b64_e32 v[62:63], 0
	v_mov_b64_e32 v[64:65], 0
	v_mov_b64_e32 v[66:67], 0
	v_mov_b64_e32 v[68:69], 0
	v_mov_b64_e32 v[70:71], 0
	v_mov_b64_e32 v[80:81], 0
	v_mov_b64_e32 v[82:83], 0
	v_mov_b64_e32 v[84:85], 0
	v_mov_b64_e32 v[86:87], 0
	v_mov_b64_e32 v[96:97], 0
	v_mov_b64_e32 v[98:99], 0
	v_mov_b64_e32 v[100:101], 0
	v_mov_b64_e32 v[102:103], 0
	v_mov_b64_e32 v[112:113], 0
	v_mov_b64_e32 v[114:115], 0
	v_mov_b64_e32 v[116:117], 0
	v_mov_b64_e32 v[118:119], 0
	v_mov_b64_e32 v[72:73], 0
	v_mov_b64_e32 v[74:75], 0
	v_mov_b64_e32 v[76:77], 0
	v_mov_b64_e32 v[78:79], 0
	v_mov_b64_e32 v[88:89], 0
	v_mov_b64_e32 v[90:91], 0
	v_mov_b64_e32 v[92:93], 0
	v_mov_b64_e32 v[94:95], 0
	v_mov_b64_e32 v[104:105], 0
	v_mov_b64_e32 v[106:107], 0
	v_mov_b64_e32 v[108:109], 0
	v_mov_b64_e32 v[110:111], 0
	v_mov_b64_e32 v[120:121], 0
	v_mov_b64_e32 v[122:123], 0
	v_mov_b64_e32 v[124:125], 0
	v_mov_b64_e32 v[126:127], 0
	s_branch .LBB0_207

; template <class Epi>
; __device__ __forceinline__ void gemm_phase(LAS unsigned char* lds, const Gemm g, const StaticOrder S, const Epi E) {
;     ...
;         const bool has_next = S.next(ui + 1, nxt);
;         const bool nrev = has_next && ((ui + 1 + g.rev0) & 1);
;         ksn = has_next ? (nrev ? -(long)kstep : (long)kstep) : ksc;
;         const char* nA = has_next ? (const char*)g.A + (size_t)nxt.pm * tstepA + (size_t)nxt.pn * g.a_pn_off + (nrev ? klast : 0) : cA;
;         const char* nB = has_next ? (const char*)g.Bt + (size_t)nxt.pn * tstepB + (nrev ? klast : 0) : cB;
;     ...
; #pragma unroll
;         for (int a = 0; a < 2; ++a)
; #pragma unroll
;             for (int b = 0; b < 2; ++b)
; #pragma unroll
;                 for (int m = 0; m < 4; ++m)
; #pragma unroll
;                     for (int n = 0; n < 2; ++n) acc[a][b][m][n] = (f32x4){0.f, 0.f, 0.f, 0.f};
.LBB0_309:
	s_and_b64 s[28:29], s[28:29], exec
	s_cselect_b32 s29, -1, 0
	s_cselect_b32 s28, 0xffffff80, s61
	s_and_b64 s[2:3], s[2:3], exec
	s_cselect_b32 s3, s29, s45
	s_cselect_b32 s2, s28, s44
	s_add_u32 s21, s42, 0x80000
	v_mov_b64_e32 v[0:1], 0
	s_mov_b32 s70, 0
	s_addc_u32 s23, s43, 0
	v_mov_b64_e32 v[2:3], 0
	v_mov_b64_e32 v[4:5], 0
	v_mov_b64_e32 v[6:7], 0
	v_mov_b64_e32 v[12:13], 0
	v_mov_b64_e32 v[14:15], 0
	v_mov_b64_e32 v[20:21], 0
	v_mov_b64_e32 v[22:23], 0
	v_mov_b64_e32 v[28:29], 0
	v_mov_b64_e32 v[30:31], 0
	v_mov_b64_e32 v[36:37], 0
	v_mov_b64_e32 v[38:39], 0
	v_mov_b64_e32 v[44:45], 0
	v_mov_b64_e32 v[46:47], 0
	v_mov_b64_e32 v[52:53], 0
	v_mov_b64_e32 v[54:55], 0
	v_mov_b64_e32 v[8:9], 0
	v_mov_b64_e32 v[10:11], 0
	v_mov_b64_e32 v[16:17], 0
	v_mov_b64_e32 v[18:19], 0
	v_mov_b64_e32 v[24:25], 0
	v_mov_b64_e32 v[26:27], 0
	v_mov_b64_e32 v[32:33], 0
	v_mov_b64_e32 v[34:35], 0
	v_mov_b64_e32 v[40:41], 0
	v_mov_b64_e32 v[42:43], 0
	v_mov_b64_e32 v[48:49], 0
	v_mov_b64_e32 v[50:51], 0
	v_mov_b64_e32 v[56:57], 0
	v_mov_b64_e32 v[58:59], 0
	v_mov_b64_e32 v[60:61], 0
	v_mov_b64_e32 v[62:63], 0
	v_mov_b64_e32 v[64:65], 0
	v_mov_b64_e32 v[66:67], 0
	v_mov_b64_e32 v[68:69], 0
	v_mov_b64_e32 v[70:71], 0
	v_mov_b64_e32 v[80:81], 0
	v_mov_b64_e32 v[82:83], 0
	v_mov_b64_e32 v[84:85], 0
	v_mov_b64_e32 v[86:87], 0
	v_mov_b64_e32 v[88:89], 0
	v_mov_b64_e32 v[90:91], 0
	v_mov_b64_e32 v[92:93], 0
	v_mov_b64_e32 v[94:95], 0
	v_mov_b64_e32 v[96:97], 0
	v_mov_b64_e32 v[98:99], 0
	v_mov_b64_e32 v[104:105], 0
	v_mov_b64_e32 v[106:107], 0
	v_mov_b64_e32 v[72:73], 0
	v_mov_b64_e32 v[74:75], 0
	v_mov_b64_e32 v[76:77], 0
	v_mov_b64_e32 v[78:79], 0
	v_mov_b64_e32 v[100:101], 0
	v_mov_b64_e32 v[102:103], 0
	v_mov_b64_e32 v[108:109], 0
	v_mov_b64_e32 v[110:111], 0
	v_mov_b64_e32 v[112:113], 0
	v_mov_b64_e32 v[114:115], 0
	v_mov_b64_e32 v[116:117], 0
	v_mov_b64_e32 v[118:119], 0
	v_mov_b64_e32 v[120:121], 0
	v_mov_b64_e32 v[122:123], 0
	v_mov_b64_e32 v[124:125], 0
	v_mov_b64_e32 v[126:127], 0
	s_branch .LBB0_311

; template <class Epi>
; __device__ __forceinline__ void gemm_phase(LAS unsigned char* lds, const Gemm g, const StaticOrder S, const Epi E) {
;     ...
;         const bool has_next = S.next(ui + 1, nxt);
;         const bool nrev = has_next && ((ui + 1 + g.rev0) & 1);
;         ksn = has_next ? (nrev ? -(long)kstep : (long)kstep) : ksc;
;         const char* nA = has_next ? (const char*)g.A + (size_t)nxt.pm * tstepA + (size_t)nxt.pn * g.a_pn_off + (nrev ? klast : 0) : cA;
;         const char* nB = has_next ? (const char*)g.Bt + (size_t)nxt.pn * tstepB + (nrev ? klast : 0) : cB;
;     ...
; #pragma unroll
;         for (int a = 0; a < 2; ++a)
; #pragma unroll
;             for (int b = 0; b < 2; ++b)
; #pragma unroll
;                 for (int m = 0; m < 4; ++m)
; #pragma unroll
;                     for (int n = 0; n < 2; ++n) acc[a][b][m][n] = (f32x4){0.f, 0.f, 0.f, 0.f};
.LBB0_565:
	s_bitcmp0_b32 s21, 0
	s_cselect_b64 s[22:23], -1, 0
	s_and_b64 s[24:25], s[22:23], s[2:3]
	s_and_b64 s[22:23], s[24:25], exec
	s_movk_i32 s19, 0xff80
	s_cselect_b32 s23, -1, 0
	s_cselect_b32 s22, s19, 0x80
	s_and_b64 s[26:27], s[2:3], exec
	s_cselect_b32 s47, s23, s45
	s_cselect_b32 s46, s22, s44
	s_ashr_i32 s21, s20, 31
	s_lshl_b64 s[26:27], s[20:21], 20
	v_readlane_b32 s48, v252, 11
	v_readlane_b32 s49, v252, 12
	s_add_u32 s19, s48, s26
	s_addc_u32 s21, s49, s27
	s_and_b64 s[24:25], s[24:25], exec
	s_cselect_b32 s50, 0xf80, 0
	s_add_u32 s24, s19, s50
	s_addc_u32 s25, s21, 0
	s_and_b64 s[26:27], s[2:3], exec
	s_cselect_b32 s49, s25, s43
	s_cselect_b32 s48, s24, s42
	s_ashr_i32 s19, s18, 31
	s_lshl_b64 s[26:27], s[18:19], 20
	v_readlane_b32 s52, v252, 9
	v_readlane_b32 s53, v252, 10
	s_add_u32 s19, s52, s26
	s_addc_u32 s21, s53, s27
	s_add_u32 s26, s19, s50
	s_addc_u32 s27, s21, 0
	s_and_b64 s[50:51], s[2:3], exec
	v_mov_b64_e32 v[0:1], 0
	s_mov_b32 s29, 0
	s_cselect_b32 s51, s27, s35
	s_cselect_b32 s50, s26, s34
	s_waitcnt lgkmcnt(0)
	v_mov_b64_e32 v[2:3], 0
	v_mov_b64_e32 v[4:5], 0
	v_mov_b64_e32 v[6:7], 0
	v_mov_b64_e32 v[16:17], 0
	v_mov_b64_e32 v[18:19], 0
	v_mov_b64_e32 v[20:21], 0
	v_mov_b64_e32 v[22:23], 0
	v_mov_b64_e32 v[32:33], 0
	v_mov_b64_e32 v[34:35], 0
	v_mov_b64_e32 v[36:37], 0
	v_mov_b64_e32 v[38:39], 0
	v_mov_b64_e32 v[48:49], 0
	v_mov_b64_e32 v[50:51], 0
	v_mov_b64_e32 v[52:53], 0
	v_mov_b64_e32 v[54:55], 0
	v_mov_b64_e32 v[8:9], 0
	v_mov_b64_e32 v[10:11], 0
	v_mov_b64_e32 v[12:13], 0
	v_mov_b64_e32 v[14:15], 0
	v_mov_b64_e32 v[24:25], 0
	v_mov_b64_e32 v[26:27], 0
	v_mov_b64_e32 v[28:29], 0
	v_mov_b64_e32 v[30:31], 0
	v_mov_b64_e32 v[40:41], 0
	v_mov_b64_e32 v[42:43], 0
	v_mov_b64_e32 v[44:45], 0
	v_mov_b64_e32 v[46:47], 0
	v_mov_b64_e32 v[56:57], 0
	v_mov_b64_e32 v[58:59], 0
	v_mov_b64_e32 v[60:61], 0
	v_mov_b64_e32 v[62:63], 0
	v_mov_b64_e32 v[64:65], 0
	v_mov_b64_e32 v[66:67], 0
	v_mov_b64_e32 v[68:69], 0
	v_mov_b64_e32 v[70:71], 0
	v_mov_b64_e32 v[80:81], 0
	v_mov_b64_e32 v[82:83], 0
	v_mov_b64_e32 v[84:85], 0
	v_mov_b64_e32 v[86:87], 0
	v_mov_b64_e32 v[96:97], 0
	v_mov_b64_e32 v[98:99], 0
	v_mov_b64_e32 v[100:101], 0
	v_mov_b64_e32 v[102:103], 0
	v_mov_b64_e32 v[112:113], 0
	v_mov_b64_e32 v[114:115], 0
	v_mov_b64_e32 v[116:117], 0
	v_mov_b64_e32 v[118:119], 0
	v_mov_b64_e32 v[72:73], 0
	v_mov_b64_e32 v[74:75], 0
	v_mov_b64_e32 v[76:77], 0
	v_mov_b64_e32 v[78:79], 0
	v_mov_b64_e32 v[88:89], 0
	v_mov_b64_e32 v[90:91], 0
	v_mov_b64_e32 v[92:93], 0
	v_mov_b64_e32 v[94:95], 0
	v_mov_b64_e32 v[104:105], 0
	v_mov_b64_e32 v[106:107], 0
	v_mov_b64_e32 v[108:109], 0
	v_mov_b64_e32 v[110:111], 0
	v_mov_b64_e32 v[120:121], 0
	v_mov_b64_e32 v[122:123], 0
	v_mov_b64_e32 v[124:125], 0
	v_mov_b64_e32 v[126:127], 0
	s_branch .LBB0_567

; template <class Epi>
; __device__ __forceinline__ void gemm_phase(LAS unsigned char* lds, const Gemm g, const StaticOrder S, const Epi E) {
;     ...
;         const bool has_next = S.next(ui + 1, nxt);
;         const bool nrev = has_next && ((ui + 1 + g.rev0) & 1);
;         ksn = has_next ? (nrev ? -(long)kstep : (long)kstep) : ksc;
;         const char* nA = has_next ? (const char*)g.A + (size_t)nxt.pm * tstepA + (size_t)nxt.pn * g.a_pn_off + (nrev ? klast : 0) : cA;
;         const char* nB = has_next ? (const char*)g.Bt + (size_t)nxt.pn * tstepB + (nrev ? klast : 0) : cB;
;     ...
; #pragma unroll
;         for (int a = 0; a < 2; ++a)
; #pragma unroll
;             for (int b = 0; b < 2; ++b)
; #pragma unroll
;                 for (int m = 0; m < 4; ++m)
; #pragma unroll
;                     for (int n = 0; n < 2; ++n) acc[a][b][m][n] = (f32x4){0.f, 0.f, 0.f, 0.f};
.LBB0_665:
	s_bitcmp0_b32 s11, 0
	s_cselect_b64 s[14:15], -1, 0
	s_and_b64 s[16:17], s[14:15], s[0:1]
	s_and_b64 s[14:15], s[16:17], exec
	s_cselect_b32 s15, -1, 0
	s_cselect_b32 s14, s60, 0x80
	s_and_b64 s[18:19], s[0:1], exec
	s_cselect_b32 s29, s15, s27
	s_cselect_b32 s28, s14, s26
	s_ashr_i32 s13, s12, 31
	s_lshl_b64 s[18:19], s[12:13], 20
	s_add_u32 s11, s76, s18
	s_addc_u32 s13, s77, s19
	s_and_b64 s[16:17], s[16:17], exec
	s_cselect_b32 s34, 0xf80, 0
	s_add_u32 s16, s11, s34
	s_addc_u32 s17, s13, 0
	s_and_b64 s[18:19], s[0:1], exec
	s_cselect_b32 s31, s17, s25
	s_cselect_b32 s30, s16, s24
	s_ashr_i32 s11, s10, 31
	s_lshl_b64 s[18:19], s[10:11], 20
	s_add_u32 s11, s33, s18
	s_addc_u32 s13, s50, s19
	s_add_u32 s18, s11, s34
	s_addc_u32 s19, s13, 0
	s_and_b64 s[34:35], s[0:1], exec
	v_mov_b64_e32 v[0:1], 0
	s_mov_b32 s66, 0
	s_cselect_b32 s35, s19, s23
	s_cselect_b32 s34, s18, s22
	v_mov_b64_e32 v[2:3], 0
	v_mov_b64_e32 v[4:5], 0
	v_mov_b64_e32 v[6:7], 0
	v_mov_b64_e32 v[16:17], 0
	v_mov_b64_e32 v[18:19], 0
	v_mov_b64_e32 v[20:21], 0
	v_mov_b64_e32 v[22:23], 0
	v_mov_b64_e32 v[32:33], 0
	v_mov_b64_e32 v[34:35], 0
	v_mov_b64_e32 v[36:37], 0
	v_mov_b64_e32 v[38:39], 0
	v_mov_b64_e32 v[48:49], 0
	v_mov_b64_e32 v[50:51], 0
	v_mov_b64_e32 v[52:53], 0
	v_mov_b64_e32 v[54:55], 0
	v_mov_b64_e32 v[8:9], 0
	v_mov_b64_e32 v[10:11], 0
	v_mov_b64_e32 v[12:13], 0
	v_mov_b64_e32 v[14:15], 0
	v_mov_b64_e32 v[24:25], 0
	v_mov_b64_e32 v[26:27], 0
	v_mov_b64_e32 v[28:29], 0
	v_mov_b64_e32 v[30:31], 0
	v_mov_b64_e32 v[40:41], 0
	v_mov_b64_e32 v[42:43], 0
	v_mov_b64_e32 v[44:45], 0
	v_mov_b64_e32 v[46:47], 0
	v_mov_b64_e32 v[56:57], 0
	v_mov_b64_e32 v[58:59], 0
	v_mov_b64_e32 v[60:61], 0
	v_mov_b64_e32 v[62:63], 0
	v_mov_b64_e32 v[64:65], 0
	v_mov_b64_e32 v[66:67], 0
	v_mov_b64_e32 v[68:69], 0
	v_mov_b64_e32 v[70:71], 0
	v_mov_b64_e32 v[80:81], 0
	v_mov_b64_e32 v[82:83], 0
	v_mov_b64_e32 v[84:85], 0
	v_mov_b64_e32 v[86:87], 0
	v_mov_b64_e32 v[96:97], 0
	v_mov_b64_e32 v[98:99], 0
	v_mov_b64_e32 v[100:101], 0
	v_mov_b64_e32 v[102:103], 0
	v_mov_b64_e32 v[120:121], 0
	v_mov_b64_e32 v[122:123], 0
	v_mov_b64_e32 v[124:125], 0
	v_mov_b64_e32 v[126:127], 0
	v_mov_b64_e32 v[72:73], 0
	v_mov_b64_e32 v[74:75], 0
	v_mov_b64_e32 v[76:77], 0
	v_mov_b64_e32 v[78:79], 0
	v_mov_b64_e32 v[88:89], 0
	v_mov_b64_e32 v[90:91], 0
	v_mov_b64_e32 v[92:93], 0
	v_mov_b64_e32 v[94:95], 0
	v_mov_b64_e32 v[104:105], 0
	v_mov_b64_e32 v[106:107], 0
	v_mov_b64_e32 v[108:109], 0
	v_mov_b64_e32 v[110:111], 0
	v_mov_b64_e32 v[112:113], 0
	v_mov_b64_e32 v[114:115], 0
	v_mov_b64_e32 v[116:117], 0
	v_mov_b64_e32 v[118:119], 0
	s_branch .LBB0_667

; template <class Epi>
; __device__ __forceinline__ void gemm_phase(LAS unsigned char* lds, const Gemm g, const StaticOrder S, const Epi E) {
;     ...
;         const bool has_next = S.next(ui + 1, nxt);
;         const bool nrev = has_next && ((ui + 1 + g.rev0) & 1);
;         ksn = has_next ? (nrev ? -(long)kstep : (long)kstep) : ksc;
;         const char* nA = has_next ? (const char*)g.A + (size_t)nxt.pm * tstepA + (size_t)nxt.pn * g.a_pn_off + (nrev ? klast : 0) : cA;
;         const char* nB = has_next ? (const char*)g.Bt + (size_t)nxt.pn * tstepB + (nrev ? klast : 0) : cB;
;     ...
; #pragma unroll
;         for (int a = 0; a < 2; ++a)
; #pragma unroll
;             for (int b = 0; b < 2; ++b)
; #pragma unroll
;                 for (int m = 0; m < 4; ++m)
; #pragma unroll
;                     for (int n = 0; n < 2; ++n) acc[a][b][m][n] = (f32x4){0.f, 0.f, 0.f, 0.f};
.LBB0_752:
	s_and_b64 s[26:27], s[26:27], exec
	s_movk_i32 s26, 0x80
	s_cselect_b32 s27, 0, -1
	s_cselect_b32 s26, s26, 0xffffff80
	s_and_b64 s[4:5], s[4:5], exec
	v_mov_b64_e32 v[0:1], 0
	s_mov_b32 s71, 0
	s_cselect_b32 s5, s27, s35
	s_cselect_b32 s4, s26, s34
	s_waitcnt lgkmcnt(0)
	v_mov_b64_e32 v[2:3], 0
	v_mov_b64_e32 v[4:5], 0
	v_mov_b64_e32 v[6:7], 0
	v_mov_b64_e32 v[16:17], 0
	v_mov_b64_e32 v[18:19], 0
	v_mov_b64_e32 v[20:21], 0
	v_mov_b64_e32 v[22:23], 0
	v_mov_b64_e32 v[32:33], 0
	v_mov_b64_e32 v[34:35], 0
	v_mov_b64_e32 v[36:37], 0
	v_mov_b64_e32 v[38:39], 0
	v_mov_b64_e32 v[48:49], 0
	v_mov_b64_e32 v[50:51], 0
	v_mov_b64_e32 v[52:53], 0
	v_mov_b64_e32 v[54:55], 0
	v_mov_b64_e32 v[8:9], 0
	v_mov_b64_e32 v[10:11], 0
	v_mov_b64_e32 v[12:13], 0
	v_mov_b64_e32 v[14:15], 0
	v_mov_b64_e32 v[24:25], 0
	v_mov_b64_e32 v[26:27], 0
	v_mov_b64_e32 v[28:29], 0
	v_mov_b64_e32 v[30:31], 0
	v_mov_b64_e32 v[40:41], 0
	v_mov_b64_e32 v[42:43], 0
	v_mov_b64_e32 v[44:45], 0
	v_mov_b64_e32 v[46:47], 0
	v_mov_b64_e32 v[56:57], 0
	v_mov_b64_e32 v[58:59], 0
	v_mov_b64_e32 v[60:61], 0
	v_mov_b64_e32 v[62:63], 0
	v_mov_b64_e32 v[64:65], 0
	v_mov_b64_e32 v[66:67], 0
	v_mov_b64_e32 v[68:69], 0
	v_mov_b64_e32 v[70:71], 0
	v_mov_b64_e32 v[80:81], 0
	v_mov_b64_e32 v[82:83], 0
	v_mov_b64_e32 v[84:85], 0
	v_mov_b64_e32 v[86:87], 0
	v_mov_b64_e32 v[96:97], 0
	v_mov_b64_e32 v[98:99], 0
	v_mov_b64_e32 v[100:101], 0
	v_mov_b64_e32 v[102:103], 0
	v_mov_b64_e32 v[112:113], 0
	v_mov_b64_e32 v[114:115], 0
	v_mov_b64_e32 v[116:117], 0
	v_mov_b64_e32 v[118:119], 0
	v_mov_b64_e32 v[72:73], 0
	v_mov_b64_e32 v[74:75], 0
	v_mov_b64_e32 v[76:77], 0
	v_mov_b64_e32 v[78:79], 0
	v_mov_b64_e32 v[88:89], 0
	v_mov_b64_e32 v[90:91], 0
	v_mov_b64_e32 v[92:93], 0
	v_mov_b64_e32 v[94:95], 0
	v_mov_b64_e32 v[104:105], 0
	v_mov_b64_e32 v[106:107], 0
	v_mov_b64_e32 v[108:109], 0
	v_mov_b64_e32 v[110:111], 0
	v_mov_b64_e32 v[120:121], 0
	v_mov_b64_e32 v[122:123], 0
	v_mov_b64_e32 v[124:125], 0
	v_mov_b64_e32 v[126:127], 0
	s_branch .LBB0_754

; template <class Epi>
; __device__ __forceinline__ void gemm_phase(LAS unsigned char* lds, const Gemm g, const StaticOrder S, const Epi E) {
;     ...
;         const bool has_next = S.next(ui + 1, nxt);
;         const bool nrev = has_next && ((ui + 1 + g.rev0) & 1);
;         ksn = has_next ? (nrev ? -(long)kstep : (long)kstep) : ksc;
;         const char* nA = has_next ? (const char*)g.A + (size_t)nxt.pm * tstepA + (size_t)nxt.pn * g.a_pn_off + (nrev ? klast : 0) : cA;
;         const char* nB = has_next ? (const char*)g.Bt + (size_t)nxt.pn * tstepB + (nrev ? klast : 0) : cB;
;     ...
; #pragma unroll
;         for (int a = 0; a < 2; ++a)
; #pragma unroll
;             for (int b = 0; b < 2; ++b)
; #pragma unroll
;                 for (int m = 0; m < 4; ++m)
; #pragma unroll
;                     for (int n = 0; n < 2; ++n) acc[a][b][m][n] = (f32x4){0.f, 0.f, 0.f, 0.f};
.LBB0_852:
	s_bitcmp0_b32 s11, 0
	s_cselect_b64 s[14:15], -1, 0
	s_and_b64 s[16:17], s[14:15], s[0:1]
	s_and_b64 s[14:15], s[16:17], exec
	s_cselect_b32 s15, -1, 0
	s_cselect_b32 s14, s58, 0x80
	s_and_b64 s[18:19], s[0:1], exec
	s_cselect_b32 s29, s15, s27
	s_cselect_b32 s28, s14, s26
	s_ashr_i32 s13, s12, 31
	s_lshl_b64 s[18:19], s[12:13], 20
	s_add_u32 s11, s76, s18
	s_addc_u32 s13, s77, s19
	s_and_b64 s[16:17], s[16:17], exec
	s_cselect_b32 s34, 0xf80, 0
	s_add_u32 s16, s11, s34
	s_addc_u32 s17, s13, 0
	s_and_b64 s[18:19], s[0:1], exec
	s_cselect_b32 s31, s17, s25
	s_cselect_b32 s30, s16, s24
	s_ashr_i32 s11, s10, 31
	s_lshl_b64 s[18:19], s[10:11], 20
	s_add_u32 s11, s82, s18
	s_addc_u32 s13, s83, s19
	s_add_u32 s18, s11, s34
	s_addc_u32 s19, s13, 0
	s_and_b64 s[34:35], s[0:1], exec
	v_mov_b64_e32 v[0:1], 0
	s_mov_b32 s64, 0
	s_cselect_b32 s35, s19, s23
	s_cselect_b32 s34, s18, s22
	v_mov_b64_e32 v[2:3], 0
	v_mov_b64_e32 v[4:5], 0
	v_mov_b64_e32 v[6:7], 0
	v_mov_b64_e32 v[16:17], 0
	v_mov_b64_e32 v[18:19], 0
	v_mov_b64_e32 v[20:21], 0
	v_mov_b64_e32 v[22:23], 0
	v_mov_b64_e32 v[32:33], 0
	v_mov_b64_e32 v[34:35], 0
	v_mov_b64_e32 v[36:37], 0
	v_mov_b64_e32 v[38:39], 0
	v_mov_b64_e32 v[48:49], 0
	v_mov_b64_e32 v[50:51], 0
	v_mov_b64_e32 v[52:53], 0
	v_mov_b64_e32 v[54:55], 0
	v_mov_b64_e32 v[8:9], 0
	v_mov_b64_e32 v[10:11], 0
	v_mov_b64_e32 v[12:13], 0
	v_mov_b64_e32 v[14:15], 0
	v_mov_b64_e32 v[24:25], 0
	v_mov_b64_e32 v[26:27], 0
	v_mov_b64_e32 v[28:29], 0
	v_mov_b64_e32 v[30:31], 0
	v_mov_b64_e32 v[40:41], 0
	v_mov_b64_e32 v[42:43], 0
	v_mov_b64_e32 v[44:45], 0
	v_mov_b64_e32 v[46:47], 0
	v_mov_b64_e32 v[56:57], 0
	v_mov_b64_e32 v[58:59], 0
	v_mov_b64_e32 v[60:61], 0
	v_mov_b64_e32 v[62:63], 0
	v_mov_b64_e32 v[64:65], 0
	v_mov_b64_e32 v[66:67], 0
	v_mov_b64_e32 v[68:69], 0
	v_mov_b64_e32 v[70:71], 0
	v_mov_b64_e32 v[80:81], 0
	v_mov_b64_e32 v[82:83], 0
	v_mov_b64_e32 v[84:85], 0
	v_mov_b64_e32 v[86:87], 0
	v_mov_b64_e32 v[96:97], 0
	v_mov_b64_e32 v[98:99], 0
	v_mov_b64_e32 v[100:101], 0
	v_mov_b64_e32 v[102:103], 0
	v_mov_b64_e32 v[120:121], 0
	v_mov_b64_e32 v[122:123], 0
	v_mov_b64_e32 v[124:125], 0
	v_mov_b64_e32 v[126:127], 0
	v_mov_b64_e32 v[72:73], 0
	v_mov_b64_e32 v[74:75], 0
	v_mov_b64_e32 v[76:77], 0
	v_mov_b64_e32 v[78:79], 0
	v_mov_b64_e32 v[88:89], 0
	v_mov_b64_e32 v[90:91], 0
	v_mov_b64_e32 v[92:93], 0
	v_mov_b64_e32 v[94:95], 0
	v_mov_b64_e32 v[104:105], 0
	v_mov_b64_e32 v[106:107], 0
	v_mov_b64_e32 v[108:109], 0
	v_mov_b64_e32 v[110:111], 0
	v_mov_b64_e32 v[112:113], 0
	v_mov_b64_e32 v[114:115], 0
	v_mov_b64_e32 v[116:117], 0
	v_mov_b64_e32 v[118:119], 0
	s_branch .LBB0_854

; template <class Epi>
; __device__ __forceinline__ void gemm_phase(LAS unsigned char* lds, const Gemm g, const StaticOrder S, const Epi E) {
;     ...
;         const bool has_next = S.next(ui + 1, nxt);
;         const bool nrev = has_next && ((ui + 1 + g.rev0) & 1);
;         ksn = has_next ? (nrev ? -(long)kstep : (long)kstep) : ksc;
;         const char* nA = has_next ? (const char*)g.A + (size_t)nxt.pm * tstepA + (size_t)nxt.pn * g.a_pn_off + (nrev ? klast : 0) : cA;
;         const char* nB = has_next ? (const char*)g.Bt + (size_t)nxt.pn * tstepB + (nrev ? klast : 0) : cB;
;     ...
; #pragma unroll
;         for (int a = 0; a < 2; ++a)
; #pragma unroll
;             for (int b = 0; b < 2; ++b)
; #pragma unroll
;                 for (int m = 0; m < 4; ++m)
; #pragma unroll
;                     for (int n = 0; n < 2; ++n) acc[a][b][m][n] = (f32x4){0.f, 0.f, 0.f, 0.f};
.LBB0_1031:
	s_bitcmp0_b32 s3, 0
	s_cselect_b64 s[18:19], -1, 0
	s_and_b64 s[20:21], s[18:19], s[0:1]
	s_and_b64 s[18:19], s[20:21], exec
	s_cselect_b32 s19, -1, 0
	s_cselect_b32 s18, s58, 0x80
	s_and_b64 s[22:23], s[0:1], exec
	s_cselect_b32 s35, s19, s31
	s_cselect_b32 s34, s18, s30
	s_ashr_i32 s17, s16, 31
	s_lshl_b64 s[22:23], s[16:17], 20
	s_add_u32 s15, s76, s22
	s_addc_u32 s17, s77, s23
	s_and_b64 s[20:21], s[20:21], exec
	s_cselect_b32 s38, 0xf80, 0
	s_add_u32 s20, s15, s38
	s_addc_u32 s21, s17, 0
	s_and_b64 s[22:23], s[0:1], exec
	s_cselect_b32 s37, s21, s29
	s_cselect_b32 s36, s20, s28
	s_ashr_i32 s15, s14, 31
	s_lshl_b64 s[22:23], s[14:15], 20
	s_add_u32 s15, s40, s22
	s_addc_u32 s17, s41, s23
	s_add_u32 s22, s15, s38
	s_addc_u32 s23, s17, 0
	s_and_b64 s[38:39], s[0:1], exec
	v_mov_b64_e32 v[0:1], 0
	s_mov_b32 s3, 0
	s_cselect_b32 s39, s23, s27
	s_cselect_b32 s38, s22, s26
	v_mov_b64_e32 v[2:3], 0
	v_mov_b64_e32 v[4:5], 0
	v_mov_b64_e32 v[6:7], 0
	v_mov_b64_e32 v[16:17], 0
	v_mov_b64_e32 v[18:19], 0
	v_mov_b64_e32 v[20:21], 0
	v_mov_b64_e32 v[22:23], 0
	v_mov_b64_e32 v[32:33], 0
	v_mov_b64_e32 v[34:35], 0
	v_mov_b64_e32 v[36:37], 0
	v_mov_b64_e32 v[38:39], 0
	v_mov_b64_e32 v[48:49], 0
	v_mov_b64_e32 v[50:51], 0
	v_mov_b64_e32 v[52:53], 0
	v_mov_b64_e32 v[54:55], 0
	v_mov_b64_e32 v[8:9], 0
	v_mov_b64_e32 v[10:11], 0
	v_mov_b64_e32 v[12:13], 0
	v_mov_b64_e32 v[14:15], 0
	v_mov_b64_e32 v[24:25], 0
	v_mov_b64_e32 v[26:27], 0
	v_mov_b64_e32 v[28:29], 0
	v_mov_b64_e32 v[30:31], 0
	v_mov_b64_e32 v[40:41], 0
	v_mov_b64_e32 v[42:43], 0
	v_mov_b64_e32 v[44:45], 0
	v_mov_b64_e32 v[46:47], 0
	v_mov_b64_e32 v[56:57], 0
	v_mov_b64_e32 v[58:59], 0
	v_mov_b64_e32 v[60:61], 0
	v_mov_b64_e32 v[62:63], 0
	v_mov_b64_e32 v[64:65], 0
	v_mov_b64_e32 v[66:67], 0
	v_mov_b64_e32 v[68:69], 0
	v_mov_b64_e32 v[70:71], 0
	v_mov_b64_e32 v[80:81], 0
	v_mov_b64_e32 v[82:83], 0
	v_mov_b64_e32 v[84:85], 0
	v_mov_b64_e32 v[86:87], 0
	v_mov_b64_e32 v[96:97], 0
	v_mov_b64_e32 v[98:99], 0
	v_mov_b64_e32 v[100:101], 0
	v_mov_b64_e32 v[102:103], 0
	v_mov_b64_e32 v[112:113], 0
	v_mov_b64_e32 v[114:115], 0
	v_mov_b64_e32 v[116:117], 0
	v_mov_b64_e32 v[118:119], 0
	v_mov_b64_e32 v[72:73], 0
	v_mov_b64_e32 v[74:75], 0
	v_mov_b64_e32 v[76:77], 0
	v_mov_b64_e32 v[78:79], 0
	v_mov_b64_e32 v[88:89], 0
	v_mov_b64_e32 v[90:91], 0
	v_mov_b64_e32 v[92:93], 0
	v_mov_b64_e32 v[94:95], 0
	v_mov_b64_e32 v[104:105], 0
	v_mov_b64_e32 v[106:107], 0
	v_mov_b64_e32 v[108:109], 0
	v_mov_b64_e32 v[110:111], 0
	v_mov_b64_e32 v[120:121], 0
	v_mov_b64_e32 v[122:123], 0
	v_mov_b64_e32 v[124:125], 0
	v_mov_b64_e32 v[126:127], 0
	s_branch .LBB0_1033

; template <class Epi>
; __device__ __forceinline__ void gemm_phase(LAS unsigned char* lds, const Gemm g, const StaticOrder S, const Epi E) {
;     ...
;         const bool has_next = S.next(ui + 1, nxt);
;         const bool nrev = has_next && ((ui + 1 + g.rev0) & 1);
;         ksn = has_next ? (nrev ? -(long)kstep : (long)kstep) : ksc;
;         const char* nA = has_next ? (const char*)g.A + (size_t)nxt.pm * tstepA + (size_t)nxt.pn * g.a_pn_off + (nrev ? klast : 0) : cA;
;         const char* nB = has_next ? (const char*)g.Bt + (size_t)nxt.pn * tstepB + (nrev ? klast : 0) : cB;
;     ...
; #pragma unroll
;         for (int a = 0; a < 2; ++a)
; #pragma unroll
;             for (int b = 0; b < 2; ++b)
; #pragma unroll
;                 for (int m = 0; m < 4; ++m)
; #pragma unroll
;                     for (int n = 0; n < 2; ++n) acc[a][b][m][n] = (f32x4){0.f, 0.f, 0.f, 0.f};
.LBB0_1372:
	s_bitcmp0_b32 s23, 0
	s_cselect_b64 s[24:25], -1, 0
	s_and_b64 s[26:27], s[24:25], s[2:3]
	s_and_b64 s[24:25], s[26:27], exec
	s_cselect_b32 s25, -1, 0
	s_cselect_b32 s24, s63, 0x80
	s_and_b64 s[28:29], s[2:3], exec
	s_cselect_b32 s43, s25, s41
	s_cselect_b32 s42, s24, s40
	s_ashr_i32 s23, s22, 31
	s_lshl_b64 s[28:29], s[22:23], 20
	v_readlane_b32 s44, v252, 11
	v_readlane_b32 s45, v252, 12
	s_add_u32 s21, s44, s28
	s_addc_u32 s23, s45, s29
	s_and_b64 s[26:27], s[26:27], exec
	s_cselect_b32 s46, 0xf80, 0
	s_add_u32 s26, s21, s46
	s_addc_u32 s27, s23, 0
	s_and_b64 s[28:29], s[2:3], exec
	s_cselect_b32 s45, s27, s39
	s_cselect_b32 s44, s26, s38
	s_ashr_i32 s21, s20, 31
	s_lshl_b64 s[28:29], s[20:21], 20
	v_readlane_b32 s48, v252, 9
	v_readlane_b32 s49, v252, 10
	s_add_u32 s21, s48, s28
	s_addc_u32 s23, s49, s29
	s_add_u32 s28, s21, s46
	s_addc_u32 s29, s23, 0
	s_and_b64 s[46:47], s[2:3], exec
	v_mov_b64_e32 v[0:1], 0
	s_mov_b32 s31, 0
	s_cselect_b32 s47, s29, s37
	s_cselect_b32 s46, s28, s36
	s_waitcnt lgkmcnt(0)
	v_mov_b64_e32 v[2:3], 0
	v_mov_b64_e32 v[4:5], 0
	v_mov_b64_e32 v[6:7], 0
	v_mov_b64_e32 v[16:17], 0
	v_mov_b64_e32 v[18:19], 0
	v_mov_b64_e32 v[20:21], 0
	v_mov_b64_e32 v[22:23], 0
	v_mov_b64_e32 v[32:33], 0
	v_mov_b64_e32 v[34:35], 0
	v_mov_b64_e32 v[36:37], 0
	v_mov_b64_e32 v[38:39], 0
	v_mov_b64_e32 v[48:49], 0
	v_mov_b64_e32 v[50:51], 0
	v_mov_b64_e32 v[52:53], 0
	v_mov_b64_e32 v[54:55], 0
	v_mov_b64_e32 v[8:9], 0
	v_mov_b64_e32 v[10:11], 0
	v_mov_b64_e32 v[12:13], 0
	v_mov_b64_e32 v[14:15], 0
	v_mov_b64_e32 v[24:25], 0
	v_mov_b64_e32 v[26:27], 0
	v_mov_b64_e32 v[28:29], 0
	v_mov_b64_e32 v[30:31], 0
	v_mov_b64_e32 v[40:41], 0
	v_mov_b64_e32 v[42:43], 0
	v_mov_b64_e32 v[44:45], 0
	v_mov_b64_e32 v[46:47], 0
	v_mov_b64_e32 v[56:57], 0
	v_mov_b64_e32 v[58:59], 0
	v_mov_b64_e32 v[60:61], 0
	v_mov_b64_e32 v[62:63], 0
	v_mov_b64_e32 v[64:65], 0
	v_mov_b64_e32 v[66:67], 0
	v_mov_b64_e32 v[68:69], 0
	v_mov_b64_e32 v[70:71], 0
	v_mov_b64_e32 v[80:81], 0
	v_mov_b64_e32 v[82:83], 0
	v_mov_b64_e32 v[84:85], 0
	v_mov_b64_e32 v[86:87], 0
	v_mov_b64_e32 v[96:97], 0
	v_mov_b64_e32 v[98:99], 0
	v_mov_b64_e32 v[100:101], 0
	v_mov_b64_e32 v[102:103], 0
	v_mov_b64_e32 v[112:113], 0
	v_mov_b64_e32 v[114:115], 0
	v_mov_b64_e32 v[116:117], 0
	v_mov_b64_e32 v[118:119], 0
	v_mov_b64_e32 v[72:73], 0
	v_mov_b64_e32 v[74:75], 0
	v_mov_b64_e32 v[76:77], 0
	v_mov_b64_e32 v[78:79], 0
	v_mov_b64_e32 v[88:89], 0
	v_mov_b64_e32 v[90:91], 0
	v_mov_b64_e32 v[92:93], 0
	v_mov_b64_e32 v[94:95], 0
	v_mov_b64_e32 v[104:105], 0
	v_mov_b64_e32 v[106:107], 0
	v_mov_b64_e32 v[108:109], 0
	v_mov_b64_e32 v[110:111], 0
	v_mov_b64_e32 v[120:121], 0
	v_mov_b64_e32 v[122:123], 0
	v_mov_b64_e32 v[124:125], 0
	v_mov_b64_e32 v[126:127], 0
	s_branch .LBB0_1374

; template <class Epi>
; __device__ __forceinline__ void gemm_phase(LAS unsigned char* lds, const Gemm g, const StaticOrder S, const Epi E) {
;     ...
;         const bool has_next = S.next(ui + 1, nxt);
;         const bool nrev = has_next && ((ui + 1 + g.rev0) & 1);
;         ksn = has_next ? (nrev ? -(long)kstep : (long)kstep) : ksc;
;         const char* nA = has_next ? (const char*)g.A + (size_t)nxt.pm * tstepA + (size_t)nxt.pn * g.a_pn_off + (nrev ? klast : 0) : cA;
;         const char* nB = has_next ? (const char*)g.Bt + (size_t)nxt.pn * tstepB + (nrev ? klast : 0) : cB;
;     ...
; #pragma unroll
;         for (int a = 0; a < 2; ++a)
; #pragma unroll
;             for (int b = 0; b < 2; ++b)
; #pragma unroll
;                 for (int m = 0; m < 4; ++m)
; #pragma unroll
;                     for (int n = 0; n < 2; ++n) acc[a][b][m][n] = (f32x4){0.f, 0.f, 0.f, 0.f};
.LBB0_1472:
	s_bitcmp0_b32 s11, 0
	s_cselect_b64 s[14:15], -1, 0
	s_and_b64 s[16:17], s[14:15], s[0:1]
	s_and_b64 s[14:15], s[16:17], exec
	s_cselect_b32 s15, -1, 0
	s_cselect_b32 s14, s54, 0x80
	s_and_b64 s[18:19], s[0:1], exec
	s_cselect_b32 s29, s15, s27
	s_cselect_b32 s28, s14, s26
	s_ashr_i32 s13, s12, 31
	s_lshl_b64 s[18:19], s[12:13], 20
	s_add_u32 s11, s76, s18
	s_addc_u32 s13, s77, s19
	s_and_b64 s[16:17], s[16:17], exec
	s_cselect_b32 s34, 0xf80, 0
	s_add_u32 s16, s11, s34
	s_addc_u32 s17, s13, 0
	s_and_b64 s[18:19], s[0:1], exec
	s_cselect_b32 s31, s17, s25
	s_cselect_b32 s30, s16, s24
	s_ashr_i32 s11, s10, 31
	s_lshl_b64 s[18:19], s[10:11], 20
	s_add_u32 s11, s33, s18
	s_addc_u32 s13, s44, s19
	s_add_u32 s18, s11, s34
	s_addc_u32 s19, s13, 0
	s_and_b64 s[34:35], s[0:1], exec
	v_mov_b64_e32 v[0:1], 0
	s_mov_b32 s60, 0
	s_cselect_b32 s35, s19, s23
	s_cselect_b32 s34, s18, s22
	v_mov_b64_e32 v[2:3], 0
	v_mov_b64_e32 v[4:5], 0
	v_mov_b64_e32 v[6:7], 0
	v_mov_b64_e32 v[16:17], 0
	v_mov_b64_e32 v[18:19], 0
	v_mov_b64_e32 v[20:21], 0
	v_mov_b64_e32 v[22:23], 0
	v_mov_b64_e32 v[32:33], 0
	v_mov_b64_e32 v[34:35], 0
	v_mov_b64_e32 v[36:37], 0
	v_mov_b64_e32 v[38:39], 0
	v_mov_b64_e32 v[48:49], 0
	v_mov_b64_e32 v[50:51], 0
	v_mov_b64_e32 v[52:53], 0
	v_mov_b64_e32 v[54:55], 0
	v_mov_b64_e32 v[8:9], 0
	v_mov_b64_e32 v[10:11], 0
	v_mov_b64_e32 v[12:13], 0
	v_mov_b64_e32 v[14:15], 0
	v_mov_b64_e32 v[24:25], 0
	v_mov_b64_e32 v[26:27], 0
	v_mov_b64_e32 v[28:29], 0
	v_mov_b64_e32 v[30:31], 0
	v_mov_b64_e32 v[40:41], 0
	v_mov_b64_e32 v[42:43], 0
	v_mov_b64_e32 v[44:45], 0
	v_mov_b64_e32 v[46:47], 0
	v_mov_b64_e32 v[56:57], 0
	v_mov_b64_e32 v[58:59], 0
	v_mov_b64_e32 v[60:61], 0
	v_mov_b64_e32 v[62:63], 0
	v_mov_b64_e32 v[64:65], 0
	v_mov_b64_e32 v[66:67], 0
	v_mov_b64_e32 v[68:69], 0
	v_mov_b64_e32 v[70:71], 0
	v_mov_b64_e32 v[80:81], 0
	v_mov_b64_e32 v[82:83], 0
	v_mov_b64_e32 v[84:85], 0
	v_mov_b64_e32 v[86:87], 0
	v_mov_b64_e32 v[96:97], 0
	v_mov_b64_e32 v[98:99], 0
	v_mov_b64_e32 v[100:101], 0
	v_mov_b64_e32 v[102:103], 0
	v_mov_b64_e32 v[120:121], 0
	v_mov_b64_e32 v[122:123], 0
	v_mov_b64_e32 v[124:125], 0
	v_mov_b64_e32 v[126:127], 0
	v_mov_b64_e32 v[72:73], 0
	v_mov_b64_e32 v[74:75], 0
	v_mov_b64_e32 v[76:77], 0
	v_mov_b64_e32 v[78:79], 0
	v_mov_b64_e32 v[88:89], 0
	v_mov_b64_e32 v[90:91], 0
	v_mov_b64_e32 v[92:93], 0
	v_mov_b64_e32 v[94:95], 0
	v_mov_b64_e32 v[104:105], 0
	v_mov_b64_e32 v[106:107], 0
	v_mov_b64_e32 v[108:109], 0
	v_mov_b64_e32 v[110:111], 0
	v_mov_b64_e32 v[112:113], 0
	v_mov_b64_e32 v[114:115], 0
	v_mov_b64_e32 v[116:117], 0
	v_mov_b64_e32 v[118:119], 0
	s_branch .LBB0_1474

; template <class Epi>
; __device__ __forceinline__ void gemm_phase(LAS unsigned char* lds, const Gemm g, const StaticOrder S, const Epi E) {
;     ...
;         const bool has_next = S.next(ui + 1, nxt);
;         const bool nrev = has_next && ((ui + 1 + g.rev0) & 1);
;         ksn = has_next ? (nrev ? -(long)kstep : (long)kstep) : ksc;
;         const char* nA = has_next ? (const char*)g.A + (size_t)nxt.pm * tstepA + (size_t)nxt.pn * g.a_pn_off + (nrev ? klast : 0) : cA;
;         const char* nB = has_next ? (const char*)g.Bt + (size_t)nxt.pn * tstepB + (nrev ? klast : 0) : cB;
;     ...
; #pragma unroll
;         for (int a = 0; a < 2; ++a)
; #pragma unroll
;             for (int b = 0; b < 2; ++b)
; #pragma unroll
;                 for (int m = 0; m < 4; ++m)
; #pragma unroll
;                     for (int n = 0; n < 2; ++n) acc[a][b][m][n] = (f32x4){0.f, 0.f, 0.f, 0.f};
.LBB0_1557:
	s_and_b64 s[26:27], s[26:27], exec
	s_cselect_b32 s27, 0, -1
	s_cselect_b32 s26, s54, 0xffffff80
	s_and_b64 s[4:5], s[4:5], exec
	v_mov_b64_e32 v[0:1], 0
	s_mov_b32 s66, 0
	s_cselect_b32 s5, s27, s35
	s_cselect_b32 s4, s26, s34
	s_waitcnt lgkmcnt(0)
	v_mov_b64_e32 v[2:3], 0
	v_mov_b64_e32 v[4:5], 0
	v_mov_b64_e32 v[6:7], 0
	v_mov_b64_e32 v[16:17], 0
	v_mov_b64_e32 v[18:19], 0
	v_mov_b64_e32 v[20:21], 0
	v_mov_b64_e32 v[22:23], 0
	v_mov_b64_e32 v[32:33], 0
	v_mov_b64_e32 v[34:35], 0
	v_mov_b64_e32 v[36:37], 0
	v_mov_b64_e32 v[38:39], 0
	v_mov_b64_e32 v[48:49], 0
	v_mov_b64_e32 v[50:51], 0
	v_mov_b64_e32 v[52:53], 0
	v_mov_b64_e32 v[54:55], 0
	v_mov_b64_e32 v[8:9], 0
	v_mov_b64_e32 v[10:11], 0
	v_mov_b64_e32 v[12:13], 0
	v_mov_b64_e32 v[14:15], 0
	v_mov_b64_e32 v[24:25], 0
	v_mov_b64_e32 v[26:27], 0
	v_mov_b64_e32 v[28:29], 0
	v_mov_b64_e32 v[30:31], 0
	v_mov_b64_e32 v[40:41], 0
	v_mov_b64_e32 v[42:43], 0
	v_mov_b64_e32 v[44:45], 0
	v_mov_b64_e32 v[46:47], 0
	v_mov_b64_e32 v[56:57], 0
	v_mov_b64_e32 v[58:59], 0
	v_mov_b64_e32 v[60:61], 0
	v_mov_b64_e32 v[62:63], 0
	v_mov_b64_e32 v[64:65], 0
	v_mov_b64_e32 v[66:67], 0
	v_mov_b64_e32 v[68:69], 0
	v_mov_b64_e32 v[70:71], 0
	v_mov_b64_e32 v[80:81], 0
	v_mov_b64_e32 v[82:83], 0
	v_mov_b64_e32 v[84:85], 0
	v_mov_b64_e32 v[86:87], 0
	v_mov_b64_e32 v[96:97], 0
	v_mov_b64_e32 v[98:99], 0
	v_mov_b64_e32 v[100:101], 0
	v_mov_b64_e32 v[102:103], 0
	v_mov_b64_e32 v[112:113], 0
	v_mov_b64_e32 v[114:115], 0
	v_mov_b64_e32 v[116:117], 0
	v_mov_b64_e32 v[118:119], 0
	v_mov_b64_e32 v[72:73], 0
	v_mov_b64_e32 v[74:75], 0
	v_mov_b64_e32 v[76:77], 0
	v_mov_b64_e32 v[78:79], 0
	v_mov_b64_e32 v[88:89], 0
	v_mov_b64_e32 v[90:91], 0
	v_mov_b64_e32 v[92:93], 0
	v_mov_b64_e32 v[94:95], 0
	v_mov_b64_e32 v[104:105], 0
	v_mov_b64_e32 v[106:107], 0
	v_mov_b64_e32 v[108:109], 0
	v_mov_b64_e32 v[110:111], 0
	v_mov_b64_e32 v[120:121], 0
	v_mov_b64_e32 v[122:123], 0
	v_mov_b64_e32 v[124:125], 0
	v_mov_b64_e32 v[126:127], 0
	s_branch .LBB0_1559
